# adds: K/V base pointer readlanes hoisted from the attention fast loop to its preheader (5 fewer issue slots per iteration)
# speedup vs baseline: 1.0024x; 1.0024x over previous
; #define LAS __attribute__((address_space(3)))
; __device__ __forceinline__ void attn_unit(const bf16* Hb, const bf16* KD, const bf16* VD, bf16* MIX, int row0, int S, int head, int qb, float lam, const float* dng, float kn0, float kn1, LAS unsigned char* lds, int wave_u) {
;     ...
;     f32x16 o[4];
; #pragma unroll
;     for (int b = 0; b < 4; ++b)
; #pragma unroll
;         for (int r = 0; r < 16; ++r) o[b][r] = 0.f;
;     const int fk = ((r32 & 3) << 2) | ((r32 >> 2) & 3);
;     const int kbase = 256 * r32 + 16 * ((c * 8 + hh) ^ fk);
;     const int q4 = (lane & 15) >> 2, pp4 = lane & 3, g1 = (lane >> 4) & 1;
;     const int vlow0 = (2 * g1 + (pp4 >> 1)) ^ hh;
;     const int vbase0 = 16384 + 256 * (4 * hh + q4) + 64 * q4 + 16 * vlow0 + 8 * (pp4 & 1);
;     const int vbase1 = 16384 + 256 * (4 * hh + q4 + 8) + 64 * q4 + 16 * (vlow0 ^ 2) + 8 * (pp4 & 1);
;     f32x2 l2 = (f32x2){0.f, 0.f};
;     ...
;     if (fast) {
;     for (int t = tlo; t <= thi; t += 2) {
;         const int pbuf = ((t - tlo) >> 1) & 1;
;         if (t + 2 <= thi) { ATT_DMA(t + 2, 2 * (pbuf ^ 1)); ATT_DMA(t + 3, 2 * (pbuf ^ 1) + 1); }
;         LAS unsigned char* BA = lds + (2 * pbuf) * TILEB;
;         LAS unsigned char* BB = BA + TILEB;
.LBB0_653:
	v_mov_b32_e32 v154, 0
	s_andn2_b64 vcc, exec, s[2:3]
	v_mov_b32_e32 v155, 0
	s_cbranch_vccnz .LBB0_677
	v_mov_b32_e32 v215, 0
	s_and_b64 vcc, exec, s[0:1]
	v_mov_b32_e32 v155, 0
	v_mov_b32_e32 v154, 0
	v_mov_b32_e32 v17, 0
	v_mov_b32_e32 v16, 0
	v_mov_b32_e32 v15, 0
	v_mov_b32_e32 v14, 0
	v_mov_b32_e32 v13, 0
	v_mov_b32_e32 v12, 0
	v_mov_b32_e32 v11, 0
	v_mov_b32_e32 v10, 0
	v_mov_b32_e32 v9, 0
	v_mov_b32_e32 v8, 0
	v_mov_b32_e32 v7, 0
	v_mov_b32_e32 v6, 0
	v_mov_b32_e32 v5, 0
	v_mov_b32_e32 v4, 0
	v_mov_b32_e32 v3, 0
	v_mov_b32_e32 v2, 0
	v_mov_b32_e32 v33, 0
	v_mov_b32_e32 v32, 0
	v_mov_b32_e32 v31, 0
	v_mov_b32_e32 v30, 0
	v_mov_b32_e32 v29, 0
	v_mov_b32_e32 v28, 0
	v_mov_b32_e32 v27, 0
	v_mov_b32_e32 v26, 0
	v_mov_b32_e32 v25, 0
	v_mov_b32_e32 v24, 0
	v_mov_b32_e32 v23, 0
	v_mov_b32_e32 v22, 0
	v_mov_b32_e32 v21, 0
	v_mov_b32_e32 v20, 0
	v_mov_b32_e32 v19, 0
	v_mov_b32_e32 v18, 0
	v_mov_b32_e32 v49, 0
	v_mov_b32_e32 v48, 0
	v_mov_b32_e32 v47, 0
	v_mov_b32_e32 v46, 0
	v_mov_b32_e32 v45, 0
	v_mov_b32_e32 v44, 0
	v_mov_b32_e32 v43, 0
	v_mov_b32_e32 v42, 0
	v_mov_b32_e32 v41, 0
	v_mov_b32_e32 v40, 0
	v_mov_b32_e32 v39, 0
	v_mov_b32_e32 v38, 0
	v_mov_b32_e32 v37, 0
	v_mov_b32_e32 v36, 0
	v_mov_b32_e32 v35, 0
	v_mov_b32_e32 v34, 0
	v_mov_b32_e32 v65, 0
	v_mov_b32_e32 v64, 0
	v_mov_b32_e32 v63, 0
	v_mov_b32_e32 v62, 0
	v_mov_b32_e32 v61, 0
	v_mov_b32_e32 v60, 0
	v_mov_b32_e32 v59, 0
	v_mov_b32_e32 v58, 0
	v_mov_b32_e32 v57, 0
	v_mov_b32_e32 v56, 0
	v_mov_b32_e32 v55, 0
	v_mov_b32_e32 v54, 0
	v_mov_b32_e32 v53, 0
	v_mov_b32_e32 v52, 0
	v_mov_b32_e32 v51, 0
	v_mov_b32_e32 v50, 0
	s_cbranch_vccnz .LBB0_677
	s_lshl_b32 s0, s73, 6
	s_sub_i32 s0, s0, s71
	v_xor_b32_e32 v174, 0x80000000, v210
	v_xor_b32_e32 v176, 0x80000000, v209
	s_sub_i32 s0, s0, s46
	v_mov_b32_e32 v50, 0
	v_xor_b32_e32 v216, 64, v213
	v_xor_b32_e32 v217, 0x4860, v141
	v_xor_b32_e32 v218, 0x80, v213
	v_xor_b32_e32 v219, 0x48a0, v141
	v_xor_b32_e32 v220, 0xc0, v213
	v_xor_b32_e32 v221, 0x48e0, v141
	v_xor_b32_e32 v222, 32, v212
	v_xor_b32_e32 v223, 64, v212
	v_xor_b32_e32 v224, 0x60, v212
	v_mov_b32_e32 v178, v174
	v_mov_b32_e32 v179, v174
	v_mov_b32_e32 v177, v176
	v_mov_b32_e32 v180, v176
	v_mov_b32_e32 v181, v176
	v_mov_b32_e32 v182, v176
	v_mov_b32_e32 v183, v176
	v_mov_b32_e32 v184, v176
	v_mov_b32_e32 v185, v176
	v_mov_b32_e32 v186, v176
	v_mov_b32_e32 v187, v176
	v_mov_b32_e32 v188, v176
	v_mov_b32_e32 v189, v176
	v_mov_b32_e32 v190, v176
	v_mov_b32_e32 v191, v176
	v_mov_b32_e32 v192, v176
	v_mov_b32_e32 v193, v176
	s_sub_i32 s33, s0, 31
	v_sub_u32_e32 v225, v140, v131
	v_add_u32_e32 v226, v139, v138
	s_mov_b32 s57, 0
	v_mov_b32_e32 v51, v50
	v_mov_b32_e32 v52, v50
	v_mov_b32_e32 v53, v50
	v_mov_b32_e32 v54, v50
	v_mov_b32_e32 v55, v50
	v_mov_b32_e32 v56, v50
	v_mov_b32_e32 v57, v50
	v_mov_b32_e32 v58, v50
	v_mov_b32_e32 v59, v50
	v_mov_b32_e32 v60, v50
	v_mov_b32_e32 v61, v50
	v_mov_b32_e32 v62, v50
	v_mov_b32_e32 v63, v50
	v_mov_b32_e32 v64, v50
	v_mov_b32_e32 v65, v50
	v_mov_b32_e32 v34, v50
	v_mov_b32_e32 v35, v50
	v_mov_b32_e32 v36, v50
	v_mov_b32_e32 v37, v50
	v_mov_b32_e32 v38, v50
	v_mov_b32_e32 v39, v50
	v_mov_b32_e32 v40, v50
	v_mov_b32_e32 v41, v50
	v_mov_b32_e32 v42, v50
	v_mov_b32_e32 v43, v50
	v_mov_b32_e32 v44, v50
	v_mov_b32_e32 v45, v50
	v_mov_b32_e32 v46, v50
	v_mov_b32_e32 v47, v50
	v_mov_b32_e32 v48, v50
	v_mov_b32_e32 v49, v50
	v_mov_b32_e32 v18, v50
	v_mov_b32_e32 v19, v50
	v_mov_b32_e32 v20, v50
	v_mov_b32_e32 v21, v50
	v_mov_b32_e32 v22, v50
	v_mov_b32_e32 v23, v50
	v_mov_b32_e32 v24, v50
	v_mov_b32_e32 v25, v50
	v_mov_b32_e32 v26, v50
	v_mov_b32_e32 v27, v50
	v_mov_b32_e32 v28, v50
	v_mov_b32_e32 v29, v50
	v_mov_b32_e32 v30, v50
	v_mov_b32_e32 v31, v50
	v_mov_b32_e32 v32, v50
	v_mov_b32_e32 v33, v50
	v_mov_b32_e32 v2, v50
	v_mov_b32_e32 v3, v50
	v_mov_b32_e32 v4, v50
	v_mov_b32_e32 v5, v50
	v_mov_b32_e32 v6, v50
	v_mov_b32_e32 v7, v50
	v_mov_b32_e32 v8, v50
	v_mov_b32_e32 v9, v50
	v_mov_b32_e32 v10, v50
	v_mov_b32_e32 v11, v50
	v_mov_b32_e32 v12, v50
	v_mov_b32_e32 v13, v50
	v_mov_b32_e32 v14, v50
	v_mov_b32_e32 v15, v50
	v_mov_b32_e32 v16, v50
	v_mov_b32_e32 v17, v50
	v_mov_b32_e32 v154, v50
	v_mov_b32_e32 v155, v50
	v_readlane_b32 s80, v251, 44
	v_readlane_b32 s81, v251, 45
	v_readlane_b32 s82, v251, 46
	v_readlane_b32 s83, v251, 47
	s_branch .LBB0_657

; __device__ __forceinline__ void attn_unit(const bf16* Hb, const bf16* KD, const bf16* VD, bf16* MIX, int row0, int S, int head, int qb, float lam, const float* dng, float kn0, float kn1, LAS unsigned char* lds, int wave_u) {
;     ...
;         if (t + 2 <= thi) { ATT_DMA(t + 2, 2 * (pbuf ^ 1)); ATT_DMA(t + 3, 2 * (pbuf ^ 1) + 1); }
.LBB0_673:
	v_add_u32_e32 v134, 0x7f, v135
	s_waitcnt lgkmcnt(0)
	v_cvt_f32_i32_e32 v172, v134
	ds_read_b64_tr_b16 v[134:135], v230 offset:4096
	ds_read_b64_tr_b16 v[136:137], v229 offset:4096
	ds_read_b64_tr_b16 v[138:139], v228 offset:4096
	ds_read_b64_tr_b16 v[140:141], v227 offset:4096
	ds_read_b64_tr_b16 v[142:143], v234 offset:4096
	ds_read_b64_tr_b16 v[144:145], v233 offset:4096
	ds_read_b64_tr_b16 v[146:147], v232 offset:4096
	ds_read_b64_tr_b16 v[148:149], v231 offset:4096
	ds_read_b128 v[194:197], v173 offset:32768
	ds_read_b128 v[238:241], v235 offset:32768
	ds_read_b128 v[242:245], v236 offset:32768
	ds_read_b128 v[246:249], v237 offset:32768
	v_mfma_f32_32x32x16_bf16 v[50:65], v[130:133], v[150:153], v[50:65]
	v_exp_f32_e32 v132, v86
	v_exp_f32_e32 v133, v87
	v_exp_f32_e32 v130, v90
	v_exp_f32_e32 v131, v91
	v_mfma_f32_32x32x16_bf16 v[34:49], v[126:129], v[150:153], v[34:49]
	v_exp_f32_e32 v126, v82
	v_exp_f32_e32 v127, v83
	v_exp_f32_e32 v128, v84
	v_exp_f32_e32 v129, v85
	v_mfma_f32_32x32x16_bf16 v[18:33], v[122:125], v[150:153], v[18:33]
	v_cvt_pk_bf16_f32 v122, v126, v127
	v_cvt_pk_bf16_f32 v123, v128, v129
	v_cvt_pk_bf16_f32 v124, v132, v133
	v_mfma_f32_32x32x16_bf16 v[2:17], v[114:117], v[150:153], v[2:17]
	v_exp_f32_e32 v152, v88
	v_exp_f32_e32 v153, v89
	v_exp_f32_e32 v150, v92
	v_exp_f32_e32 v151, v93
	v_cvt_pk_bf16_f32 v125, v152, v153
	v_cvt_pk_bf16_f32 v114, v130, v131
	v_cvt_pk_bf16_f32 v115, v150, v151
	s_waitcnt lgkmcnt(0)
	v_mfma_f32_32x32x16_bf16 v[66:81], v[194:197], v[98:101], v[66:81]
	v_exp_f32_e32 v194, v94
	v_exp_f32_e32 v195, v95
	v_exp_f32_e32 v196, v96
	v_exp_f32_e32 v197, v97
	v_cvt_pk_bf16_f32 v116, v194, v195
	v_cvt_pk_bf16_f32 v117, v196, v197
	v_mfma_f32_32x32x16_bf16 v[66:81], v[238:241], v[102:105], v[66:81]
	v_mfma_f32_32x32x16_bf16 v[66:81], v[242:245], v[106:109], v[66:81]
	v_mfma_f32_32x32x16_bf16 v[66:81], v[246:249], v[110:113], v[66:81]
	s_cmp_le_i32 s73, s74
	s_cbranch_scc0 .Ldma_skip_0
	s_xor_b32 s84, s59, 0x10000
	s_add_i32 s84, s76, s84
	v_add_u32_e32 v250, s75, v226
	v_add_u32_e32 v254, s75, v211
	v_add_u32_e32 v250, 0x8000, v250
	v_add_u32_e32 v254, 0x8000, v254
	s_add_i32 m0, s84, 0x0
	s_nop 0
	global_load_lds_dwordx4 v250, s[80:81]
	s_add_i32 m0, s84, 0x400
	s_nop 0
	global_load_lds_dwordx4 v254, s[80:81]
	s_add_i32 m0, s84, 0x4000
	s_nop 0
	global_load_lds_dwordx4 v250, s[82:83]
	s_add_i32 m0, s84, 0x4400
	s_nop 0
	global_load_lds_dwordx4 v254, s[82:83]
